# MLA attention loop: all K fragment reads issued early, V reads behind them, restaging and global loads behind the first reads (on top of the diff-loop changes)
# baseline (speedup 1.0000x reference)
.LBB0_190:
	s_bitcmp1_b32 s1, 0
	s_cselect_b32 s0, 0x5400, 0
	v_add3_u32 v185, s0, v192, v159
	ds_read_b128 v[186:189], v185
	ds_read_b128 v[194:197], v185 offset:64
	ds_read_b128 v[202:205], v185 offset:128
	ds_read_b128 v[112:115], v185 offset:832
	ds_read_b128 v[108:111], v185 offset:896
	ds_read_b128 v[104:107], v185 offset:960
	v_add_u32_e32 v100, s0, v174
	v_add3_u32 v100, v100, v175, v176
	v_add_u32_e32 v184, v100, v177
	v_add_u32_e32 v183, v100, v178
	v_add_u32_e32 v182, v100, v179
	v_add_u32_e32 v181, v100, v180
	ds_read_b128 v[100:103], v185 offset:6656
	ds_read_b128 v[144:147], v185 offset:6720
	ds_read_b128 v[128:131], v185 offset:6784
	s_andn2_b32 s0, 1, s1
	s_mulk_i32 s0, 0x5400
	s_add_i32 s10, s1, 1
	v_add3_u32 v140, s0, v151, v155
	v_add3_u32 v141, s0, v157, v170
	v_add_u32_e32 v142, s0, v171
	s_waitcnt vmcnt(2)
	ds_write_b128 v140, v[8:11]
	v_add3_u32 v142, v142, v173, v172
	s_add_i32 s0, s1, 3
	s_min_u32 s0, s0, s83
	s_waitcnt vmcnt(0)
	ds_write_b128 v141, v[28:31]
	s_lshl_b32 s0, s0, 6
	ds_write_b128 v142, v[32:35] offset:13312
	v_add_u32_e32 v8, s0, v154
	v_add_u32_e32 v28, s0, v156
	s_add_i32 s0, s1, 2
	v_ashrrev_i32_e32 v9, 31, v8
	v_ashrrev_i32_e32 v29, 31, v28
	s_min_u32 s0, s0, s83
	v_lshlrev_b64 v[10:11], 11, v[8:9]
	v_lshlrev_b64 v[8:9], 6, v[8:9]
	v_lshlrev_b64 v[30:31], 11, v[28:29]
	v_lshlrev_b64 v[28:29], 6, v[28:29]
	v_lshl_add_u32 v32, s0, 6, v158
	v_lshl_add_u64 v[8:9], v[162:163], 0, v[8:9]
	v_lshl_add_u64 v[28:29], v[166:167], 0, v[28:29]
	v_ashrrev_i32_e32 v33, 31, v32
	v_lshl_add_u64 v[10:11], v[164:165], 0, v[10:11]
	v_lshl_add_u64 v[8:9], v[8:9], 0, s[58:59]
	v_lshl_add_u64 v[30:31], v[168:169], 0, v[30:31]
	v_lshl_add_u64 v[28:29], v[28:29], 0, s[58:59]
	v_lshlrev_b64 v[32:33], 11, v[32:33]
	v_cndmask_b32_e64 v9, v9, v11, s[6:7]
	v_cndmask_b32_e64 v8, v8, v10, s[6:7]
	v_cndmask_b32_e64 v29, v29, v31, s[8:9]
	v_cndmask_b32_e64 v28, v28, v30, s[8:9]
	v_lshl_add_u64 v[32:33], v[160:161], 0, v[32:33]
	global_load_dwordx4 v[8:11], v[8:9], off
	global_load_dwordx4 v[28:31], v[28:29], off
	global_load_dwordx4 v[32:35], v[32:33], off offset:128
	s_waitcnt lgkmcnt(11)
	v_mfma_f32_16x16x32_bf16 v[136:139], v[186:189], v[12:15], v[36:39]
	v_mfma_f32_16x16x32_bf16 v[120:123], v[186:189], v[20:23], v[48:51]
	ds_read_b128 v[186:189], v185 offset:7488
	s_waitcnt lgkmcnt(11)
	v_mfma_f32_16x16x32_bf16 v[136:139], v[194:197], v[16:19], v[136:139]
	v_mfma_f32_16x16x32_bf16 v[120:123], v[194:197], v[24:27], v[120:123]
	ds_read_b128 v[194:197], v185 offset:7552
	s_waitcnt lgkmcnt(11)
	v_mfma_f32_16x16x32_bf16 v[136:139], v[202:205], v[0:3], v[136:139]
	v_mfma_f32_16x16x32_bf16 v[120:123], v[202:205], v[4:7], v[120:123]
	ds_read_b128 v[202:205], v185 offset:7616
	s_waitcnt lgkmcnt(11)
	v_mfma_f32_16x16x32_bf16 v[132:135], v[112:115], v[12:15], v[36:39]
	v_mfma_f32_16x16x32_bf16 v[116:119], v[112:115], v[20:23], v[48:51]
	ds_read_b64_tr_b16 v[112:113], v184 offset:13312
	ds_read_b64_tr_b16 v[114:115], v184 offset:13824
	s_waitcnt lgkmcnt(12)
	v_mfma_f32_16x16x32_bf16 v[132:135], v[108:111], v[16:19], v[132:135]
	v_mfma_f32_16x16x32_bf16 v[116:119], v[108:111], v[24:27], v[116:119]
	ds_read_b64_tr_b16 v[108:109], v183 offset:13312
	ds_read_b64_tr_b16 v[110:111], v183 offset:13824
	s_waitcnt lgkmcnt(13)
	v_mfma_f32_16x16x32_bf16 v[132:135], v[104:107], v[0:3], v[132:135]
	v_mfma_f32_16x16x32_bf16 v[116:119], v[104:107], v[4:7], v[116:119]
	ds_read_b64_tr_b16 v[104:105], v182 offset:13312
	ds_read_b64_tr_b16 v[106:107], v182 offset:13824
	s_waitcnt lgkmcnt(14)
	v_mfma_f32_16x16x32_bf16 v[140:143], v[100:103], v[12:15], v[36:39]
	v_mfma_f32_16x16x32_bf16 v[124:127], v[100:103], v[20:23], v[48:51]
	ds_read_b64_tr_b16 v[100:101], v181 offset:13312
	ds_read_b64_tr_b16 v[102:103], v181 offset:13824
	s_waitcnt lgkmcnt(15)
	v_mfma_f32_16x16x32_bf16 v[140:143], v[144:147], v[16:19], v[140:143]
	v_mfma_f32_16x16x32_bf16 v[124:127], v[144:147], v[24:27], v[124:127]
	s_waitcnt lgkmcnt(14)
	v_mfma_f32_16x16x32_bf16 v[140:143], v[128:131], v[0:3], v[140:143]
	v_mfma_f32_16x16x32_bf16 v[124:127], v[128:131], v[4:7], v[124:127]
	s_waitcnt lgkmcnt(10)
	v_mfma_f32_16x16x32_bf16 v[144:147], v[186:189], v[12:15], v[36:39]
	v_mfma_f32_16x16x32_bf16 v[128:131], v[186:189], v[20:23], v[48:51]
	s_waitcnt lgkmcnt(9)
	v_mfma_f32_16x16x32_bf16 v[144:147], v[194:197], v[16:19], v[144:147]
	v_mfma_f32_16x16x32_bf16 v[128:131], v[194:197], v[24:27], v[128:131]
	s_waitcnt lgkmcnt(8)
	v_mfma_f32_16x16x32_bf16 v[144:147], v[202:205], v[0:3], v[144:147]
	v_mfma_f32_16x16x32_bf16 v[128:131], v[202:205], v[4:7], v[128:131]
	s_cmp_ge_u32 s10, s82
	s_cbranch_scc1 .LBB0_196
	s_cmp_lg_u32 s1, 0
	s_cselect_b64 s[0:1], -1, 0
	s_and_b32 s11, s10, 3
	s_cmp_lg_u32 s11, 0
	s_cselect_b64 s[14:15], -1, 0
	s_and_b64 s[0:1], s[0:1], s[14:15]
	s_and_b64 vcc, exec, s[0:1]
	s_cbranch_vccnz .LBB0_196
	v_max_f32_e32 v185, v137, v137
	v_max_f32_e32 v186, v136, v136
	v_max_f32_e32 v185, v186, v185
	v_max3_f32 v185, v185, v138, v139
	v_max3_f32 v185, v185, v132, v133
	v_max3_f32 v185, v185, v134, v135
	v_max3_f32 v185, v185, v140, v141
	v_max3_f32 v185, v185, v142, v143
	v_max3_f32 v185, v185, v144, v145
	v_max3_f32 v185, v185, v146, v147
	v_mov_b32_e32 v186, v185
	s_nop 1
	v_permlane16_swap_b32_e32 v185, v186
	v_max_f32_e32 v186, v186, v186
	v_max_f32_e32 v185, v185, v185
	v_max_f32_e32 v185, v185, v186
	v_mov_b32_e32 v186, v185
	s_nop 1
	v_permlane32_swap_b32_e32 v185, v186
	v_max_f32_e32 v186, v186, v186
	v_max_f32_e32 v185, v185, v185
	v_max_f32_e32 v185, v185, v186
	v_cmp_lt_f32_e32 vcc, s44, v185
	s_cbranch_vccz .LBB0_194
	s_nop 0
	v_cndmask_b32_e32 v185, 0, v185, vcc
	v_exp_f32_e64 v186, -v185
	v_lshlrev_b32_e32 v188, 16, v56
	v_and_b32_e32 v189, 0xffff0000, v56
	v_sub_f32_e32 v139, v139, v185
	v_pk_mul_f32 v[188:189], v[186:187], v[188:189] op_sel_hi:[0,1]
	v_cvt_pk_bf16_f32 v56, v188, v189
	v_lshlrev_b32_e32 v188, 16, v57
	v_and_b32_e32 v189, 0xffff0000, v57
	v_pk_mul_f32 v[188:189], v[186:187], v[188:189] op_sel_hi:[0,1]
	v_cvt_pk_bf16_f32 v57, v188, v189
	v_lshlrev_b32_e32 v188, 16, v58
	v_and_b32_e32 v189, 0xffff0000, v58
	v_pk_mul_f32 v[188:189], v[186:187], v[188:189] op_sel_hi:[0,1]
	v_cvt_pk_bf16_f32 v58, v188, v189
	v_lshlrev_b32_e32 v188, 16, v59
	v_and_b32_e32 v189, 0xffff0000, v59
	v_pk_mul_f32 v[188:189], v[186:187], v[188:189] op_sel_hi:[0,1]
	v_cvt_pk_bf16_f32 v59, v188, v189
	v_lshlrev_b32_e32 v188, 16, v52
	v_and_b32_e32 v189, 0xffff0000, v52
	v_pk_mul_f32 v[188:189], v[186:187], v[188:189] op_sel_hi:[0,1]
	v_cvt_pk_bf16_f32 v52, v188, v189
	v_lshlrev_b32_e32 v188, 16, v53
	v_and_b32_e32 v189, 0xffff0000, v53
	v_pk_mul_f32 v[188:189], v[186:187], v[188:189] op_sel_hi:[0,1]
	v_cvt_pk_bf16_f32 v53, v188, v189
	v_lshlrev_b32_e32 v188, 16, v54
	v_and_b32_e32 v189, 0xffff0000, v54
	v_pk_mul_f32 v[188:189], v[186:187], v[188:189] op_sel_hi:[0,1]
	v_cvt_pk_bf16_f32 v54, v188, v189
	v_lshlrev_b32_e32 v188, 16, v55
	v_and_b32_e32 v189, 0xffff0000, v55
	v_pk_mul_f32 v[78:79], v[78:79], v[186:187] op_sel_hi:[1,0]
	v_pk_mul_f32 v[76:77], v[76:77], v[186:187] op_sel_hi:[1,0]
	v_pk_mul_f32 v[98:99], v[98:99], v[186:187] op_sel_hi:[1,0]
	v_pk_mul_f32 v[96:97], v[96:97], v[186:187] op_sel_hi:[1,0]
	v_pk_mul_f32 v[94:95], v[94:95], v[186:187] op_sel_hi:[1,0]
	v_pk_mul_f32 v[92:93], v[92:93], v[186:187] op_sel_hi:[1,0]
	v_pk_mul_f32 v[86:87], v[86:87], v[186:187] op_sel_hi:[1,0]
	v_pk_mul_f32 v[84:85], v[84:85], v[186:187] op_sel_hi:[1,0]
	v_pk_mul_f32 v[42:43], v[42:43], v[186:187] op_sel_hi:[1,0]
	v_pk_mul_f32 v[40:41], v[40:41], v[186:187] op_sel_hi:[1,0]
	v_pk_mul_f32 v[186:187], v[186:187], v[188:189] op_sel_hi:[0,1]
	v_sub_f32_e32 v138, v138, v185
	v_sub_f32_e32 v137, v137, v185
	v_sub_f32_e32 v136, v136, v185
	v_sub_f32_e32 v135, v135, v185
	v_sub_f32_e32 v134, v134, v185
	v_sub_f32_e32 v133, v133, v185
	v_sub_f32_e32 v132, v132, v185
	v_sub_f32_e32 v143, v143, v185
	v_sub_f32_e32 v142, v142, v185
	v_sub_f32_e32 v141, v141, v185
	v_sub_f32_e32 v140, v140, v185
	v_sub_f32_e32 v147, v147, v185
	v_sub_f32_e32 v146, v146, v185
	v_sub_f32_e32 v145, v145, v185
	v_sub_f32_e32 v144, v144, v185
	v_cvt_pk_bf16_f32 v55, v186, v187
	v_sub_f32_e32 v39, v39, v185
	v_sub_f32_e32 v38, v38, v185
	v_sub_f32_e32 v37, v37, v185
	v_sub_f32_e32 v36, v36, v185

.LBB0_196:
	s_waitcnt lgkmcnt(6)
	v_mfma_f32_16x16x32_bf16 v[96:99], v[112:115], v[56:59], v[96:99]
	v_exp_f32_e32 v136, v136
	v_exp_f32_e32 v137, v137
	v_exp_f32_e32 v138, v138
	v_mfma_f32_16x16x32_bf16 v[88:91], v[112:115], v[68:71], v[88:91]
	ds_read_b64_tr_b16 v[112:113], v184 offset:17408
	ds_read_b64_tr_b16 v[114:115], v184 offset:17920
	v_exp_f32_e32 v139, v139
	s_waitcnt lgkmcnt(6)
	v_mfma_f32_16x16x32_bf16 v[92:95], v[108:111], v[56:59], v[92:95]
	v_exp_f32_e32 v184, v133
	v_exp_f32_e32 v185, v134
	v_exp_f32_e32 v186, v135
	v_mfma_f32_16x16x32_bf16 v[80:83], v[108:111], v[68:71], v[80:83]
	ds_read_b64_tr_b16 v[108:109], v183 offset:17408
	ds_read_b64_tr_b16 v[110:111], v183 offset:17920
	v_exp_f32_e32 v183, v132
	s_waitcnt lgkmcnt(6)
	v_mfma_f32_16x16x32_bf16 v[84:87], v[104:107], v[56:59], v[84:87]
	v_exp_f32_e32 v140, v140
	v_exp_f32_e32 v141, v141
	v_exp_f32_e32 v142, v142
	v_mfma_f32_16x16x32_bf16 v[72:75], v[104:107], v[68:71], v[72:75]
	ds_read_b64_tr_b16 v[104:105], v182 offset:17408
	ds_read_b64_tr_b16 v[106:107], v182 offset:17920
	v_exp_f32_e32 v143, v143
	s_mov_b32 s30, s28
	s_mov_b32 s31, s28
	s_mov_b32 s29, s28
	v_mov_b64_e32 v[134:135], s[30:31]
	v_mov_b64_e32 v[132:133], s[28:29]
	s_waitcnt lgkmcnt(6)
	v_mfma_f32_16x16x32_bf16 v[40:43], v[100:103], v[56:59], v[40:43]
	v_exp_f32_e32 v144, v144
	v_exp_f32_e32 v145, v145
	v_exp_f32_e32 v146, v146
	v_mfma_f32_16x16x32_bf16 v[44:47], v[100:103], v[68:71], v[44:47]
	ds_read_b64_tr_b16 v[100:101], v181 offset:17408
	ds_read_b64_tr_b16 v[102:103], v181 offset:17920
	v_exp_f32_e32 v147, v147
	v_mfma_f32_16x16x32_bf16 v[76:79], v[132:135], v[56:59], v[76:79]
	v_mfma_f32_16x16x32_bf16 v[60:63], v[132:135], v[68:71], v[60:63]
	v_exp_f32_e32 v68, v120
	v_exp_f32_e32 v69, v121
	s_waitcnt lgkmcnt(6)
	v_mfma_f32_16x16x32_bf16 v[96:99], v[112:115], v[52:55], v[96:99]
	v_exp_f32_e32 v70, v122
	v_exp_f32_e32 v71, v123
	v_cvt_pk_bf16_f32 v56, v136, v137
	v_mfma_f32_16x16x32_bf16 v[88:91], v[112:115], v[64:67], v[88:91]
	v_cvt_pk_bf16_f32 v57, v138, v139
	v_cvt_pk_bf16_f32 v58, v183, v184
	v_cvt_pk_bf16_f32 v59, v185, v186
	s_waitcnt lgkmcnt(4)
	v_mfma_f32_16x16x32_bf16 v[92:95], v[108:111], v[52:55], v[92:95]
	v_exp_f32_e32 v112, v116
	v_exp_f32_e32 v113, v117
	v_exp_f32_e32 v114, v118
	v_mfma_f32_16x16x32_bf16 v[80:83], v[108:111], v[64:67], v[80:83]
	v_exp_f32_e32 v115, v119
	s_waitcnt lgkmcnt(2)
	v_mfma_f32_16x16x32_bf16 v[84:87], v[104:107], v[52:55], v[84:87]
	v_cvt_pk_bf16_f32 v68, v68, v69
	v_cvt_pk_bf16_f32 v69, v70, v71
	v_cvt_pk_bf16_f32 v70, v112, v113
	v_mfma_f32_16x16x32_bf16 v[72:75], v[104:107], v[64:67], v[72:75]
	v_cvt_pk_bf16_f32 v71, v114, v115
	v_exp_f32_e32 v108, v124
	v_exp_f32_e32 v109, v125
	v_exp_f32_e32 v110, v126
	v_exp_f32_e32 v111, v127
	s_waitcnt lgkmcnt(0)
	v_mfma_f32_16x16x32_bf16 v[40:43], v[100:103], v[52:55], v[40:43]
	v_exp_f32_e32 v104, v128
	v_exp_f32_e32 v105, v129
	v_exp_f32_e32 v106, v130
	v_mfma_f32_16x16x32_bf16 v[44:47], v[100:103], v[64:67], v[44:47]
	v_exp_f32_e32 v107, v131
	v_mfma_f32_16x16x32_bf16 v[76:79], v[132:135], v[52:55], v[76:79]
	v_mfma_f32_16x16x32_bf16 v[60:63], v[132:135], v[64:67], v[60:63]
	s_waitcnt lgkmcnt(0)
	s_barrier
	v_cvt_pk_bf16_f32 v52, v140, v141
	v_cvt_pk_bf16_f32 v53, v142, v143
	v_cvt_pk_bf16_f32 v54, v144, v145
	v_cvt_pk_bf16_f32 v55, v146, v147
	v_cvt_pk_bf16_f32 v64, v108, v109
	v_cvt_pk_bf16_f32 v65, v110, v111
	v_cvt_pk_bf16_f32 v66, v104, v105
	v_cvt_pk_bf16_f32 v67, v106, v107
	s_cmp_lg_u32 s82, s10
	s_cbranch_scc0 .LBB0_156
	s_mov_b32 s1, s10
	s_branch .LBB0_190
